# stick-breaking work map: workgroups of one (batch,head) share an XCD L2; up-projection epilogue second-half row scales loaded with the first half
# speedup vs baseline: 1.0089x; 1.0089x over previous
;   DI void operator()(const f32x4 (&acc)[2][2][4][2], const Unit& u, int wr, int wc, int fr, int fq) const {
;     const int f0 = u.pn * 128 + wc * 32 + 8 * fq;
;     f32x4 w0[2], w1[2], w2[2], bb[2];
; #pragma unroll
;     for (int n = 0; n < 2; ++n) { w0[n] = *(const f32x4*)(cw + f0 + 4 * n); w1[n] = *(const f32x4*)(cw + D_FF + f0 + 4 * n); w2[n] = *(const f32x4*)(cw + 2 * D_FF + f0 + 4 * n); bb[n] = *(const f32x4*)(cb + f0 + 4 * n); }
; #pragma unroll
;     for (int ai = 0; ai < 2; ++ai) {
;       const int blk = u.pm * 4 + ai * 2 + wr;
;       const int rowb = blk * 64;
;       float rr[4];
; #pragma unroll
;       for (int m = 0; m < 4; ++m) rr[m] = rrow[rowb + m * 16 + fr];
;       f32x4 Gp[2] = {(f32x4){0.f, 0.f, 0.f, 0.f}, (f32x4){0.f, 0.f, 0.f, 0.f}};
; #pragma unroll
;       for (int m = 0; m < 4; ++m) {
;         float o[2][4];
;         f32x4 G[2];
; #pragma unroll
;         for (int n = 0; n < 2; ++n) G[n] = acc[ai][0][m][n] * rr[m];
; #pragma unroll
;         for (int n = 0; n < 2; ++n)
; #pragma unroll
;           for (int j = 0; j < 4; ++j) {
;             const float g0 = G[n][j], gp = Gp[n][j];
;             const float g1 = dpp_shr_or(dpp_ror(gp, 1), g0, 1);
;             const float g2 = dpp_shr_or(dpp_ror(gp, 2), g0, 2);
.LBB0_482:
	v_lshl_or_b32 v174, s25, 7, v194
	s_lshl_b32 s22, s24, 2
	v_ashrrev_i32_e32 v175, 31, v174
	s_add_i32 vcc_lo, s22, s46
	v_lshlrev_b64 v[176:177], 2, v[174:175]
	v_lshl_or_b32 v192, vcc_lo, 6, v166
	v_lshl_add_u64 v[24:25], s[40:41], 0, v[176:177]
	v_lshl_add_u64 v[26:27], s[62:63], 0, v[176:177]
	v_lshl_add_u64 v[52:53], s[64:65], 0, v[176:177]
	v_lshl_add_u64 v[54:55], s[42:43], 0, v[176:177]
	v_ashrrev_i32_e32 v193, 31, v192
	v_or_b32_e32 v186, 16, v192
	global_load_dwordx4 v[36:39], v[24:25], off
	global_load_dwordx4 v[60:63], v[24:25], off offset:16
	global_load_dwordx4 v[40:43], v[26:27], off
	global_load_dwordx4 v[64:67], v[26:27], off offset:16
	global_load_dwordx4 v[44:47], v[52:53], off
	global_load_dwordx4 v[68:71], v[52:53], off offset:16
	s_nop 0
	global_load_dwordx4 v[24:27], v[54:55], off
	s_nop 0
	global_load_dwordx4 v[52:55], v[54:55], off offset:16
	v_lshl_add_u64 v[178:179], v[192:193], 2, s[20:21]
	v_ashrrev_i32_e32 v187, 31, v186
	v_or_b32_e32 v182, 32, v192
	global_load_dword v224, v[178:179], off offset:512
	global_load_dword v190, v[178:179], off
	v_lshl_add_u64 v[178:179], v[186:187], 2, s[20:21]
	v_ashrrev_i32_e32 v183, 31, v182
	global_load_dword v225, v[178:179], off offset:512
	global_load_dword v188, v[178:179], off
	v_lshl_add_u64 v[178:179], v[182:183], 2, s[20:21]
	global_load_dword v226, v[178:179], off offset:512
	global_load_dword v184, v[178:179], off
	v_or_b32_e32 v178, 48, v192
	v_ashrrev_i32_e32 v179, 31, v178
	v_lshl_add_u64 v[180:181], v[178:179], 2, s[20:21]
	global_load_dword v227, v[180:181], off offset:512
	global_load_dword v180, v[180:181], off
	v_mov_b32_dpp v201, v209 row_ror:2 row_mask:0xf bank_mask:0xf
	v_mov_b32_e32 v181, v201
	v_mov_b32_e32 v185, v201
	v_mov_b32_e32 v189, v201
	v_mov_b32_e32 v196, v201
	v_mov_b32_e32 v198, v201
	v_mov_b32_e32 v200, v201
	v_mov_b32_e32 v203, v201
	s_waitcnt vmcnt(0)
	v_pk_mul_f32 v[158:159], v[158:159], v[190:191] op_sel_hi:[1,0]
	v_pk_mul_f32 v[156:157], v[156:157], v[190:191] op_sel_hi:[1,0]
	v_pk_mul_f32 v[154:155], v[154:155], v[190:191] op_sel_hi:[1,0]
	v_pk_mul_f32 v[152:153], v[152:153], v[190:191] op_sel_hi:[1,0]
	v_mov_b32_dpp v191, v209 row_ror:1 row_mask:0xf bank_mask:0xf
	v_mov_b32_e32 v179, v191
	v_mov_b32_e32 v183, v191
	v_mov_b32_e32 v187, v191
	v_mov_b32_e32 v193, v191
	v_mov_b32_e32 v197, v191
	v_mov_b32_e32 v199, v191
	v_mov_b32_e32 v202, v191
	v_mov_b32_dpp v179, v156 row_shr:1 row_mask:0xf bank_mask:0xf
	v_mov_b32_dpp v181, v156 row_shr:2 row_mask:0xf bank_mask:0xf
	v_mov_b32_dpp v183, v157 row_shr:1 row_mask:0xf bank_mask:0xf
	v_mov_b32_dpp v185, v157 row_shr:2 row_mask:0xf bank_mask:0xf
	v_mov_b32_dpp v187, v158 row_shr:1 row_mask:0xf bank_mask:0xf
	v_mov_b32_dpp v189, v158 row_shr:2 row_mask:0xf bank_mask:0xf
	v_mov_b32_dpp v193, v159 row_shr:1 row_mask:0xf bank_mask:0xf
	v_mov_b32_dpp v196, v159 row_shr:2 row_mask:0xf bank_mask:0xf
	v_mov_b32_dpp v197, v152 row_shr:1 row_mask:0xf bank_mask:0xf
	v_mov_b32_dpp v198, v152 row_shr:2 row_mask:0xf bank_mask:0xf
	v_mov_b32_dpp v199, v153 row_shr:1 row_mask:0xf bank_mask:0xf
	v_mov_b32_dpp v200, v153 row_shr:2 row_mask:0xf bank_mask:0xf
	v_mov_b32_dpp v202, v154 row_shr:1 row_mask:0xf bank_mask:0xf
	v_mov_b32_dpp v203, v154 row_shr:2 row_mask:0xf bank_mask:0xf
	v_mov_b32_dpp v191, v155 row_shr:1 row_mask:0xf bank_mask:0xf
	v_mov_b32_dpp v201, v155 row_shr:2 row_mask:0xf bank_mask:0xf
	s_and_saveexec_b64 s[22:23], s[34:35]
	s_xor_b64 s[22:23], exec, s[22:23]
	s_cbranch_execz .LBB0_484
; DI unsigned cvt_pk_bf16(float lo, float hi) { unsigned r; asm volatile("v_cvt_pk_bf16_f32 %0, %1, %2" : "=v"(r) : "v"(lo), "v"(hi)); return r; }
;   DI void operator()(const f32x4 (&acc)[2][2][4][2], const Unit& u, int wr, int wc, int fr, int fq) const {
;     ...
;             const float g0 = G[n][j], gp = Gp[n][j];
;             const float g1 = dpp_shr_or(dpp_ror(gp, 1), g0, 1);
;             const float g2 = dpp_shr_or(dpp_ror(gp, 2), g0, 2);
;             const float cv = __builtin_fmaf(w2[n][j], g0, __builtin_fmaf(w1[n][j], g1, __builtin_fmaf(w0[n][j], g2, bb[n][j])));
;             o[n][j] = gelu_tanh(cv) * (acc[ai][1][m][n][j] * rr[m]);
;           }
;         const bool head = (m == 0) && (fr < 2);
;         if (!head) { u32x4 w; w.x = cvt_pk_bf16(o[0][0], o[0][1]); w.y = cvt_pk_bf16(o[0][2], o[0][3]); w.z = cvt_pk_bf16(o[1][0], o[1][1]); w.w = cvt_pk_bf16(o[1][2], o[1][3]);
;           *(u32x4*)(act + (size_t)(rowb + m * 16 + fr) * D_FF + f0) = w; }
	v_fma_f32 v205, v63, v201, v55
	v_fmac_f32_e32 v205, v67, v191
	v_fmac_f32_e32 v205, v71, v155
	v_mul_f32_e32 v191, v205, v205
	v_fmamk_f32 v191, v191, 0xbdd2d3e6, v236
	v_mul_f32_e32 v191, v205, v191
	v_exp_f32_e32 v191, v191
	v_fma_f32 v203, v62, v203, v54
	v_fmac_f32_e32 v203, v66, v202
	v_mov_b32_e32 v204, v139
	v_add_f32_e32 v191, 1.0, v191
	v_rcp_f32_e32 v191, v191
	v_fmac_f32_e32 v203, v70, v154
	v_fma_f32 v201, v61, v200, v53
	v_fmac_f32_e32 v201, v65, v199
	v_pk_mul_f32 v[204:205], v[204:205], v[190:191]
	v_mul_f32_e32 v191, v203, v203
	v_fmamk_f32 v191, v191, 0xbdd2d3e6, v236
	v_mul_f32_e32 v191, v203, v191
	v_exp_f32_e32 v191, v191
	v_mov_b32_e32 v202, v138
	v_fmac_f32_e32 v201, v69, v153
	v_fma_f32 v199, v60, v198, v52
	v_add_f32_e32 v191, 1.0, v191
	v_rcp_f32_e32 v191, v191
	v_fmac_f32_e32 v199, v64, v197
	v_mov_b32_e32 v200, v137
	v_fmac_f32_e32 v199, v68, v152
	v_pk_mul_f32 v[202:203], v[202:203], v[190:191]
	v_mul_f32_e32 v191, v201, v201
	v_fmamk_f32 v191, v191, 0xbdd2d3e6, v236
	v_mul_f32_e32 v191, v201, v191
	v_exp_f32_e32 v191, v191
	v_fma_f32 v197, v39, v196, v27
	v_fmac_f32_e32 v197, v43, v193
	v_mov_b32_e32 v198, v136
	v_add_f32_e32 v191, 1.0, v191
	v_rcp_f32_e32 v191, v191
	v_fmac_f32_e32 v197, v47, v159
	v_mov_b32_e32 v196, v147
	s_movk_i32 s24, 0x2c00
	v_pk_mul_f32 v[200:201], v[200:201], v[190:191]
	v_mul_f32_e32 v191, v199, v199
	v_fmamk_f32 v191, v191, 0xbdd2d3e6, v236
	v_mul_f32_e32 v191, v199, v191
	v_exp_f32_e32 v191, v191
	v_mul_f32_e32 v204, v204, v205
	v_mul_f32_e32 v202, v202, v203
	v_mul_f32_e32 v200, v200, v201
	v_add_f32_e32 v191, 1.0, v191
	v_rcp_f32_e32 v191, v191
	s_nop 0
	v_pk_mul_f32 v[198:199], v[198:199], v[190:191]
	v_mul_f32_e32 v191, v197, v197
	v_fmamk_f32 v191, v191, 0xbdd2d3e6, v236
	v_mul_f32_e32 v191, v197, v191
	v_exp_f32_e32 v191, v191
	v_mul_f32_e32 v198, v198, v199
	v_add_f32_e32 v191, 1.0, v191
	v_rcp_f32_e32 v191, v191
	s_nop 0
	v_pk_mul_f32 v[196:197], v[196:197], v[190:191]
	s_nop 0
	v_mul_f32_e32 v193, v196, v197
	v_fma_f32 v197, v38, v189, v26
	v_fmac_f32_e32 v197, v42, v187
	v_fmac_f32_e32 v197, v46, v158
	v_mul_f32_e32 v187, v197, v197
	v_fmamk_f32 v187, v187, 0xbdd2d3e6, v236
	v_mul_f32_e32 v187, v197, v187
	v_exp_f32_e32 v187, v187
	v_mov_b32_e32 v196, v146
	v_add_f32_e32 v187, 1.0, v187
	v_rcp_f32_e32 v191, v187
	s_nop 0
	v_pk_mul_f32 v[196:197], v[196:197], v[190:191]
	s_nop 0
	v_mul_f32_e32 v187, v196, v197
	v_fma_f32 v197, v37, v185, v25
	v_fmac_f32_e32 v197, v41, v183
	v_fmac_f32_e32 v197, v45, v157
	v_mul_f32_e32 v183, v197, v197
	v_fmamk_f32 v183, v183, 0xbdd2d3e6, v236
	v_mul_f32_e32 v183, v197, v183
	v_exp_f32_e32 v183, v183
	v_mov_b32_e32 v196, v145
	v_add_f32_e32 v183, 1.0, v183
	v_rcp_f32_e32 v191, v183
	s_nop 0
	v_pk_mul_f32 v[196:197], v[196:197], v[190:191]
	s_nop 0
	v_mul_f32_e32 v183, v196, v197
	v_fma_f32 v197, v36, v181, v24
	v_fmac_f32_e32 v197, v40, v179
	v_fmac_f32_e32 v197, v44, v156
	v_mul_f32_e32 v179, v197, v197
	v_fmamk_f32 v179, v179, 0xbdd2d3e6, v236
	v_mul_f32_e32 v179, v197, v179
	v_exp_f32_e32 v179, v179
	v_mov_b32_e32 v196, v144
	v_add_f32_e32 v179, 1.0, v179
	v_rcp_f32_e32 v191, v179
	s_nop 0
	v_pk_mul_f32 v[190:191], v[196:197], v[190:191]
	s_nop 0
	v_mul_f32_e32 v179, v190, v191
	v_mov_b64_e32 v[190:191], s[30:31]
	v_mad_i64_i32 v[190:191], s[24:25], v192, s24, v[190:191]
	v_lshl_add_u64 v[190:191], v[174:175], 1, v[190:191]
	v_cvt_pk_bf16_f32 v196, v179, v183
	v_cvt_pk_bf16_f32 v197, v187, v193
	v_cvt_pk_bf16_f32 v198, v198, v200
	v_cvt_pk_bf16_f32 v199, v202, v204
	global_store_dwordx4 v[190:191], v[196:199], off

; DI unsigned cvt_pk_bf16(float lo, float hi) { unsigned r; asm volatile("v_cvt_pk_bf16_f32 %0, %1, %2" : "=v"(r) : "v"(lo), "v"(hi)); return r; }
;   DI void operator()(const f32x4 (&acc)[2][2][4][2], const Unit& u, int wr, int wc, int fr, int fq) const {
;     ...
;     for (int ai = 0; ai < 2; ++ai) {
;       const int blk = u.pm * 4 + ai * 2 + wr;
;       const int rowb = blk * 64;
;       float rr[4];
; #pragma unroll
;       for (int m = 0; m < 4; ++m) rr[m] = rrow[rowb + m * 16 + fr];
;       f32x4 Gp[2] = {(f32x4){0.f, 0.f, 0.f, 0.f}, (f32x4){0.f, 0.f, 0.f, 0.f}};
; #pragma unroll
;       for (int m = 0; m < 4; ++m) {
;         float o[2][4];
;         f32x4 G[2];
; #pragma unroll
;         for (int n = 0; n < 2; ++n) G[n] = acc[ai][0][m][n] * rr[m];
; #pragma unroll
;         for (int n = 0; n < 2; ++n)
; #pragma unroll
;           for (int j = 0; j < 4; ++j) {
;             const float g0 = G[n][j], gp = Gp[n][j];
;             const float g1 = dpp_shr_or(dpp_ror(gp, 1), g0, 1);
;             const float g2 = dpp_shr_or(dpp_ror(gp, 2), g0, 2);
;             const float cv = __builtin_fmaf(w2[n][j], g0, __builtin_fmaf(w1[n][j], g1, __builtin_fmaf(w0[n][j], g2, bb[n][j])));
;             o[n][j] = gelu_tanh(cv) * (acc[ai][1][m][n][j] * rr[m]);
;           }
;         const bool head = (m == 0) && (fr < 2);
;         if (!head) { u32x4 w; w.x = cvt_pk_bf16(o[0][0], o[0][1]); w.y = cvt_pk_bf16(o[0][2], o[0][3]); w.z = cvt_pk_bf16(o[1][0], o[1][1]); w.w = cvt_pk_bf16(o[1][2], o[1][3]);
;           *(u32x4*)(act + (size_t)(rowb + m * 16 + fr) * D_FF + f0) = w; }
.LBB0_488:
	s_or_b64 exec, exec, s[22:23]
	s_add_i32 s22, vcc_lo, 2
	v_lshl_or_b32 v110, s22, 6, v166
	v_ashrrev_i32_e32 v111, 31, v110
	v_or_b32_e32 v104, 16, v110
	v_lshl_add_u64 v[96:97], v[110:111], 2, s[20:21]
	v_ashrrev_i32_e32 v105, 31, v104
	v_or_b32_e32 v100, 32, v110
	v_mov_b32_e32 v108, v224
	v_lshl_add_u64 v[96:97], v[104:105], 2, s[20:21]
	v_ashrrev_i32_e32 v101, 31, v100
	v_mov_b32_e32 v106, v225
	v_lshl_add_u64 v[96:97], v[100:101], 2, s[20:21]
	v_mov_b32_e32 v102, v226
	v_or_b32_e32 v96, 48, v110
	v_ashrrev_i32_e32 v97, 31, v96
	v_lshl_add_u64 v[98:99], v[96:97], 2, s[20:21]
	v_mov_b32_e32 v98, v227
	v_mov_b32_dpp v117, v209 row_ror:2 row_mask:0xf bank_mask:0xf
	v_mov_b32_e32 v99, v117
	v_mov_b32_e32 v103, v117
	v_mov_b32_e32 v107, v117
	v_mov_b32_e32 v112, v117
	v_mov_b32_e32 v114, v117
	v_mov_b32_e32 v116, v117
	v_mov_b32_e32 v119, v117
	v_pk_mul_f32 v[94:95], v[94:95], v[108:109] op_sel_hi:[1,0]
	v_pk_mul_f32 v[92:93], v[92:93], v[108:109] op_sel_hi:[1,0]
	v_pk_mul_f32 v[90:91], v[90:91], v[108:109] op_sel_hi:[1,0]
	v_pk_mul_f32 v[88:89], v[88:89], v[108:109] op_sel_hi:[1,0]
	v_mov_b32_dpp v109, v209 row_ror:1 row_mask:0xf bank_mask:0xf
	v_mov_b32_e32 v97, v109
	v_mov_b32_e32 v101, v109
	v_mov_b32_e32 v105, v109
	v_mov_b32_e32 v111, v109
	v_mov_b32_e32 v113, v109
	v_mov_b32_e32 v115, v109
	v_mov_b32_e32 v118, v109
	v_mov_b32_dpp v97, v92 row_shr:1 row_mask:0xf bank_mask:0xf
	v_mov_b32_dpp v99, v92 row_shr:2 row_mask:0xf bank_mask:0xf
	v_mov_b32_dpp v101, v93 row_shr:1 row_mask:0xf bank_mask:0xf
	v_mov_b32_dpp v103, v93 row_shr:2 row_mask:0xf bank_mask:0xf
	v_mov_b32_dpp v105, v94 row_shr:1 row_mask:0xf bank_mask:0xf
	v_mov_b32_dpp v107, v94 row_shr:2 row_mask:0xf bank_mask:0xf
	v_mov_b32_dpp v111, v95 row_shr:1 row_mask:0xf bank_mask:0xf
	v_mov_b32_dpp v112, v95 row_shr:2 row_mask:0xf bank_mask:0xf
	v_mov_b32_dpp v113, v88 row_shr:1 row_mask:0xf bank_mask:0xf
	v_mov_b32_dpp v114, v88 row_shr:2 row_mask:0xf bank_mask:0xf
	v_mov_b32_dpp v115, v89 row_shr:1 row_mask:0xf bank_mask:0xf
	v_mov_b32_dpp v116, v89 row_shr:2 row_mask:0xf bank_mask:0xf
	v_mov_b32_dpp v118, v90 row_shr:1 row_mask:0xf bank_mask:0xf
	v_mov_b32_dpp v119, v90 row_shr:2 row_mask:0xf bank_mask:0xf
	v_mov_b32_dpp v109, v91 row_shr:1 row_mask:0xf bank_mask:0xf
	v_mov_b32_dpp v117, v91 row_shr:2 row_mask:0xf bank_mask:0xf
	s_and_saveexec_b64 s[24:25], s[34:35]
	s_xor_b64 s[24:25], exec, s[24:25]
	s_cbranch_execz .LBB0_490
	v_fma_f32 v121, v63, v117, v55
	v_fmac_f32_e32 v121, v67, v109
	v_fmac_f32_e32 v121, v71, v91
	v_mul_f32_e32 v109, v121, v121
	v_fmamk_f32 v109, v109, 0xbdd2d3e6, v236
	v_mul_f32_e32 v109, v121, v109
	v_exp_f32_e32 v109, v109
	v_fma_f32 v119, v62, v119, v54
	v_fmac_f32_e32 v119, v66, v118
	v_mov_b32_e32 v120, v75
	v_add_f32_e32 v109, 1.0, v109
	v_rcp_f32_e32 v109, v109
	v_fmac_f32_e32 v119, v70, v90
	v_fma_f32 v117, v61, v116, v53
	v_fmac_f32_e32 v117, v65, v115
	v_pk_mul_f32 v[120:121], v[120:121], v[108:109]
	v_mul_f32_e32 v109, v119, v119
	v_fmamk_f32 v109, v109, 0xbdd2d3e6, v236
	v_mul_f32_e32 v109, v119, v109
	v_exp_f32_e32 v109, v109
	v_mov_b32_e32 v118, v74
	v_fmac_f32_e32 v117, v69, v89
	v_fma_f32 v115, v60, v114, v52
	v_add_f32_e32 v109, 1.0, v109
	v_rcp_f32_e32 v109, v109
	v_fmac_f32_e32 v115, v64, v113
	v_mov_b32_e32 v116, v73
	v_fmac_f32_e32 v115, v68, v88
	v_pk_mul_f32 v[118:119], v[118:119], v[108:109]
	v_mul_f32_e32 v109, v117, v117
	v_fmamk_f32 v109, v109, 0xbdd2d3e6, v236
	v_mul_f32_e32 v109, v117, v109
	v_exp_f32_e32 v109, v109
	v_fma_f32 v113, v39, v112, v27
	v_fmac_f32_e32 v113, v43, v111
	v_mov_b32_e32 v114, v72
	v_add_f32_e32 v109, 1.0, v109
	v_rcp_f32_e32 v109, v109
	v_fmac_f32_e32 v113, v47, v95
	v_mov_b32_e32 v112, v83
	v_mul_f32_e32 v120, v120, v121
	v_pk_mul_f32 v[116:117], v[116:117], v[108:109]
	v_mul_f32_e32 v109, v115, v115
	v_fmamk_f32 v109, v109, 0xbdd2d3e6, v236
	v_mul_f32_e32 v109, v115, v109
	v_exp_f32_e32 v109, v109
	v_mul_f32_e32 v118, v118, v119
	v_mul_f32_e32 v116, v116, v117
	v_add_f32_e32 v109, 1.0, v109
	v_rcp_f32_e32 v109, v109
	s_nop 0
	v_pk_mul_f32 v[114:115], v[114:115], v[108:109]
	v_mul_f32_e32 v109, v113, v113
	v_fmamk_f32 v109, v109, 0xbdd2d3e6, v236
	v_mul_f32_e32 v109, v113, v109
	v_exp_f32_e32 v109, v109
	v_mul_f32_e32 v114, v114, v115
	v_add_f32_e32 v109, 1.0, v109
	v_rcp_f32_e32 v109, v109
	s_nop 0
	v_pk_mul_f32 v[112:113], v[112:113], v[108:109]
	s_nop 0
	v_mul_f32_e32 v111, v112, v113
	v_fma_f32 v113, v38, v107, v26
	v_fmac_f32_e32 v113, v42, v105
	v_fmac_f32_e32 v113, v46, v94
	v_mul_f32_e32 v105, v113, v113
	v_fmamk_f32 v105, v105, 0xbdd2d3e6, v236
	v_mul_f32_e32 v105, v113, v105
	v_exp_f32_e32 v105, v105
	v_mov_b32_e32 v112, v82
	v_add_f32_e32 v105, 1.0, v105
	v_rcp_f32_e32 v109, v105
	s_nop 0
	v_pk_mul_f32 v[112:113], v[112:113], v[108:109]
	s_nop 0
	v_mul_f32_e32 v105, v112, v113
	v_fma_f32 v113, v37, v103, v25
	v_fmac_f32_e32 v113, v41, v101
	v_fmac_f32_e32 v113, v45, v93
	v_mul_f32_e32 v101, v113, v113
	v_fmamk_f32 v101, v101, 0xbdd2d3e6, v236
	v_mul_f32_e32 v101, v113, v101
	v_exp_f32_e32 v101, v101
	v_mov_b32_e32 v112, v81
	v_add_f32_e32 v101, 1.0, v101
	v_rcp_f32_e32 v109, v101
	s_nop 0
	v_pk_mul_f32 v[112:113], v[112:113], v[108:109]
	s_nop 0
	v_mul_f32_e32 v101, v112, v113
	v_fma_f32 v113, v36, v99, v24
	v_fmac_f32_e32 v113, v40, v97
	v_fmac_f32_e32 v113, v44, v92
	v_mul_f32_e32 v97, v113, v113
	v_fmamk_f32 v97, v97, 0xbdd2d3e6, v236
	v_mul_f32_e32 v97, v113, v97
	v_exp_f32_e32 v97, v97
	v_mov_b32_e32 v112, v80
	v_add_f32_e32 v97, 1.0, v97
	v_rcp_f32_e32 v109, v97
	s_nop 0
	v_pk_mul_f32 v[108:109], v[112:113], v[108:109]
	s_nop 0
	v_mul_f32_e32 v97, v108, v109
	v_mov_b64_e32 v[108:109], s[30:31]
	v_mad_i64_i32 v[108:109], s[26:27], v110, s44, v[108:109]
	v_lshl_add_u64 v[108:109], v[174:175], 1, v[108:109]
	v_cvt_pk_bf16_f32 v112, v97, v101
	v_cvt_pk_bf16_f32 v113, v105, v111
	v_cvt_pk_bf16_f32 v114, v114, v116
	v_cvt_pk_bf16_f32 v115, v118, v120
	global_store_dwordx4 v[108:109], v[112:115], off

; DI unsigned cvt_pk_bf16(float lo, float hi) { unsigned r; asm volatile("v_cvt_pk_bf16_f32 %0, %1, %2" : "=v"(r) : "v"(lo), "v"(hi)); return r; }
;   DI void operator()(const f32x4 (&acc)[2][2][4][2], const Unit& u, int wr, int wc, int fr, int fq) const {
;     ...
;       for (int m = 0; m < 4; ++m) {
;         float o[2][4];
;         f32x4 G[2];
; #pragma unroll
;         for (int n = 0; n < 2; ++n) G[n] = acc[ai][0][m][n] * rr[m];
; #pragma unroll
;         for (int n = 0; n < 2; ++n)
; #pragma unroll
;           for (int j = 0; j < 4; ++j) {
;             const float g0 = G[n][j], gp = Gp[n][j];
;             const float g1 = dpp_shr_or(dpp_ror(gp, 1), g0, 1);
;             const float g2 = dpp_shr_or(dpp_ror(gp, 2), g0, 2);
;             const float cv = __builtin_fmaf(w2[n][j], g0, __builtin_fmaf(w1[n][j], g1, __builtin_fmaf(w0[n][j], g2, bb[n][j])));
;             o[n][j] = gelu_tanh(cv) * (acc[ai][1][m][n][j] * rr[m]);
;           }
;         const bool head = (m == 0) && (fr < 2);
;         if (!head) { u32x4 w; w.x = cvt_pk_bf16(o[0][0], o[0][1]); w.y = cvt_pk_bf16(o[0][2], o[0][3]); w.z = cvt_pk_bf16(o[1][0], o[1][1]); w.w = cvt_pk_bf16(o[1][2], o[1][3]);
;           *(u32x4*)(act + (size_t)(rowb + m * 16 + fr) * D_FF + f0) = w; }
;         if (m == 0 && fr < 2) { float* hg = headg + ((size_t)blk * 2 + fr) * D_FF + f0; float* hv = headv + ((size_t)blk * 2 + fr) * D_FF + f0;
;           *(f32x4*)hg = G[0]; *(f32x4*)(hg + 4) = G[1]; *(f32x4*)hv = acc[ai][1][0][0] * rr[0]; *(f32x4*)(hv + 4) = acc[ai][1][0][1] * rr[0]; }
;         if (m == 3 && fr >= 14) { float* tg = tailg + ((size_t)blk * 2 + (fr - 14)) * D_FF + f0;
;           *(f32x4*)tg = G[0]; *(f32x4*)(tg + 4) = G[1]; }
;         Gp[0] = G[0]; Gp[1] = G[1];
.LBB0_492:
	s_or_b64 exec, exec, s[26:27]
	v_pk_mul_f32 v[72:73], v[78:79], v[106:107] op_sel_hi:[1,0]
	v_pk_mul_f32 v[74:75], v[76:77], v[106:107] op_sel_hi:[1,0]
	v_mov_b32_dpp v77, v91 row_ror:2 row_mask:0xf bank_mask:0xf
	v_mov_b32_dpp v76, v91 row_ror:1 row_mask:0xf bank_mask:0xf
	v_pk_mul_f32 v[80:81], v[86:87], v[106:107] op_sel_hi:[1,0]
	v_mov_b32_dpp v77, v73 row_shr:2 row_mask:0xf bank_mask:0xf
	v_mov_b32_dpp v76, v73 row_shr:1 row_mask:0xf bank_mask:0xf
	v_fma_f32 v77, v63, v77, v55
	v_fmac_f32_e32 v77, v67, v76
	v_fmac_f32_e32 v77, v71, v73
	v_mul_f32_e32 v76, v77, v77
	v_fmamk_f32 v76, v76, 0xbdd2d3e6, v236
	v_mul_f32_e32 v76, v77, v76
	v_exp_f32_e32 v76, v76
	v_pk_mul_f32 v[82:83], v[84:85], v[106:107] op_sel_hi:[1,0]
	v_mov_b32_dpp v97, v90 row_ror:1 row_mask:0xf bank_mask:0xf
	v_mov_b32_dpp v90, v90 row_ror:2 row_mask:0xf bank_mask:0xf
	v_add_f32_e32 v76, 1.0, v76
	v_rcp_f32_e32 v107, v76
	v_mov_b32_dpp v90, v72 row_shr:2 row_mask:0xf bank_mask:0xf
	v_mov_b32_dpp v97, v72 row_shr:1 row_mask:0xf bank_mask:0xf
	v_mov_b32_e32 v76, v59
	v_fma_f32 v59, v62, v90, v54
	v_fmac_f32_e32 v59, v66, v97
	v_pk_mul_f32 v[76:77], v[76:77], v[106:107]
	v_fmac_f32_e32 v59, v70, v72
	v_mul_f32_e32 v76, v76, v77
	v_mul_f32_e32 v77, v59, v59
	v_fmamk_f32 v77, v77, 0xbdd2d3e6, v236
	v_mul_f32_e32 v77, v59, v77
	v_exp_f32_e32 v77, v77
	v_mov_b32_dpp v78, v92 row_ror:1 row_mask:0xf bank_mask:0xf
	v_mov_b32_dpp v79, v92 row_ror:2 row_mask:0xf bank_mask:0xf
	v_mov_b32_dpp v84, v93 row_ror:1 row_mask:0xf bank_mask:0xf
	v_add_f32_e32 v77, 1.0, v77
	v_rcp_f32_e32 v107, v77
	v_mov_b32_dpp v85, v93 row_ror:2 row_mask:0xf bank_mask:0xf
	v_mov_b32_dpp v92, v95 row_ror:1 row_mask:0xf bank_mask:0xf
	v_mov_b32_dpp v93, v95 row_ror:2 row_mask:0xf bank_mask:0xf
	v_mov_b32_dpp v95, v89 row_ror:1 row_mask:0xf bank_mask:0xf
	v_mov_b32_dpp v89, v89 row_ror:2 row_mask:0xf bank_mask:0xf
	v_pk_mul_f32 v[58:59], v[58:59], v[106:107]
	v_mov_b32_dpp v95, v75 row_shr:1 row_mask:0xf bank_mask:0xf
	v_mov_b32_dpp v89, v75 row_shr:2 row_mask:0xf bank_mask:0xf
	v_mul_f32_e32 v77, v58, v59
	v_fma_f32 v59, v61, v89, v53
	v_fmac_f32_e32 v59, v65, v95
	v_fmac_f32_e32 v59, v69, v75
	v_mul_f32_e32 v58, v59, v59
	v_fmamk_f32 v58, v58, 0xbdd2d3e6, v236
	v_mul_f32_e32 v58, v59, v58
	v_exp_f32_e32 v58, v58
	v_mov_b32_dpp v86, v94 row_ror:1 row_mask:0xf bank_mask:0xf
	v_mov_b32_dpp v87, v94 row_ror:2 row_mask:0xf bank_mask:0xf
	v_mov_b32_dpp v94, v88 row_ror:1 row_mask:0xf bank_mask:0xf
	v_add_f32_e32 v58, 1.0, v58
	v_mov_b32_dpp v88, v88 row_ror:2 row_mask:0xf bank_mask:0xf
	v_rcp_f32_e32 v107, v58
	v_mov_b32_dpp v94, v74 row_shr:1 row_mask:0xf bank_mask:0xf
	v_mov_b32_dpp v88, v74 row_shr:2 row_mask:0xf bank_mask:0xf
	v_mov_b32_e32 v58, v57
	v_fma_f32 v57, v60, v88, v52
	v_fmac_f32_e32 v57, v64, v94
	v_pk_mul_f32 v[58:59], v[58:59], v[106:107]
	v_fmac_f32_e32 v57, v68, v74
	v_mul_f32_e32 v58, v58, v59
	v_mul_f32_e32 v59, v57, v57
	v_fmamk_f32 v59, v59, 0xbdd2d3e6, v236
	v_mul_f32_e32 v59, v57, v59
	v_exp_f32_e32 v59, v59
	v_mov_b32_dpp v93, v81 row_shr:2 row_mask:0xf bank_mask:0xf
	v_mov_b32_dpp v92, v81 row_shr:1 row_mask:0xf bank_mask:0xf
	v_mov_b32_dpp v87, v80 row_shr:2 row_mask:0xf bank_mask:0xf
	v_add_f32_e32 v59, 1.0, v59
	v_rcp_f32_e32 v107, v59
	v_mov_b32_dpp v86, v80 row_shr:1 row_mask:0xf bank_mask:0xf
	v_mov_b32_dpp v85, v83 row_shr:2 row_mask:0xf bank_mask:0xf
	v_mov_b32_dpp v84, v83 row_shr:1 row_mask:0xf bank_mask:0xf
	v_pk_mul_f32 v[56:57], v[56:57], v[106:107]
	v_mov_b32_dpp v79, v82 row_shr:2 row_mask:0xf bank_mask:0xf
	v_mul_f32_e32 v59, v56, v57
	v_fma_f32 v57, v39, v93, v27
	v_fmac_f32_e32 v57, v43, v92
	v_fmac_f32_e32 v57, v47, v81
	v_mul_f32_e32 v56, v57, v57
	v_fmamk_f32 v56, v56, 0xbdd2d3e6, v236
	v_mul_f32_e32 v56, v57, v56
	v_exp_f32_e32 v56, v56
	v_mov_b32_dpp v78, v82 row_shr:1 row_mask:0xf bank_mask:0xf
	s_movk_i32 s26, 0x2c00
	v_pk_mul_f32 v[30:31], v[30:31], v[102:103] op_sel_hi:[1,0]
	v_add_f32_e32 v56, 1.0, v56
	v_rcp_f32_e32 v107, v56
	v_mov_b32_e32 v56, v35
	v_fma_f32 v35, v38, v87, v26
	v_fmac_f32_e32 v35, v42, v86
	v_pk_mul_f32 v[56:57], v[56:57], v[106:107]
	v_fmac_f32_e32 v35, v46, v80
	v_mul_f32_e32 v57, v56, v57
	v_mul_f32_e32 v56, v35, v35
	v_fmamk_f32 v56, v56, 0xbdd2d3e6, v236
	v_mul_f32_e32 v56, v35, v56
	v_exp_f32_e32 v56, v56
	v_pk_mul_f32 v[48:49], v[48:49], v[102:103] op_sel_hi:[1,0]
	v_pk_mul_f32 v[28:29], v[28:29], v[102:103] op_sel_hi:[1,0]
	v_pk_mul_f32 v[10:11], v[10:11], v[98:99] op_sel_hi:[1,0]
	v_add_f32_e32 v56, 1.0, v56
	v_rcp_f32_e32 v107, v56
	v_pk_mul_f32 v[8:9], v[8:9], v[98:99] op_sel_hi:[1,0]
	v_pk_mul_f32 v[34:35], v[34:35], v[106:107]
	s_nop 0
	v_mul_f32_e32 v86, v34, v35
	v_fma_f32 v35, v37, v85, v25
	v_fmac_f32_e32 v35, v41, v84
	v_fmac_f32_e32 v35, v45, v83
	v_mul_f32_e32 v34, v35, v35
	v_fmamk_f32 v34, v34, 0xbdd2d3e6, v236
	v_mul_f32_e32 v34, v35, v34
	v_exp_f32_e32 v34, v34
	s_nop 0
	v_add_f32_e32 v34, 1.0, v34
	v_rcp_f32_e32 v107, v34
	v_mov_b32_e32 v34, v33
	v_fma_f32 v33, v36, v79, v24
	v_fmac_f32_e32 v33, v40, v78
	v_pk_mul_f32 v[34:35], v[34:35], v[106:107]
	v_fmac_f32_e32 v33, v44, v82
	v_mul_f32_e32 v34, v34, v35
	v_mul_f32_e32 v35, v33, v33
	v_fmamk_f32 v35, v35, 0xbdd2d3e6, v236
	v_mul_f32_e32 v35, v33, v35
	v_exp_f32_e32 v35, v35
	v_mov_b32_dpp v78, v81 row_ror:1 row_mask:0xf bank_mask:0xf
	v_mov_b32_dpp v79, v81 row_ror:2 row_mask:0xf bank_mask:0xf
	v_mov_b32_dpp v81, v75 row_ror:1 row_mask:0xf bank_mask:0xf
	v_add_f32_e32 v35, 1.0, v35
	v_rcp_f32_e32 v107, v35
	v_mov_b32_dpp v75, v75 row_ror:2 row_mask:0xf bank_mask:0xf
	v_mov_b32_dpp v81, v29 row_shr:1 row_mask:0xf bank_mask:0xf
; DI unsigned cvt_pk_bf16(float lo, float hi) { unsigned r; asm volatile("v_cvt_pk_bf16_f32 %0, %1, %2" : "=v"(r) : "v"(lo), "v"(hi)); return r; }
;   DI void operator()(const f32x4 (&acc)[2][2][4][2], const Unit& u, int wr, int wc, int fr, int fq) const {
;     ...
;       for (int m = 0; m < 4; ++m) {
;         float o[2][4];
;         f32x4 G[2];
; #pragma unroll
;         for (int n = 0; n < 2; ++n) G[n] = acc[ai][0][m][n] * rr[m];
; #pragma unroll
;         for (int n = 0; n < 2; ++n)
; #pragma unroll
;           for (int j = 0; j < 4; ++j) {
;             const float g0 = G[n][j], gp = Gp[n][j];
;             const float g1 = dpp_shr_or(dpp_ror(gp, 1), g0, 1);
;             const float g2 = dpp_shr_or(dpp_ror(gp, 2), g0, 2);
;             const float cv = __builtin_fmaf(w2[n][j], g0, __builtin_fmaf(w1[n][j], g1, __builtin_fmaf(w0[n][j], g2, bb[n][j])));
;             o[n][j] = gelu_tanh(cv) * (acc[ai][1][m][n][j] * rr[m]);
;           }
;         const bool head = (m == 0) && (fr < 2);
;         if (!head) { u32x4 w; w.x = cvt_pk_bf16(o[0][0], o[0][1]); w.y = cvt_pk_bf16(o[0][2], o[0][3]); w.z = cvt_pk_bf16(o[1][0], o[1][1]); w.w = cvt_pk_bf16(o[1][2], o[1][3]);
;           *(u32x4*)(act + (size_t)(rowb + m * 16 + fr) * D_FF + f0) = w; }
;         if (m == 0 && fr < 2) { float* hg = headg + ((size_t)blk * 2 + fr) * D_FF + f0; float* hv = headv + ((size_t)blk * 2 + fr) * D_FF + f0;
;           *(f32x4*)hg = G[0]; *(f32x4*)(hg + 4) = G[1]; *(f32x4*)hv = acc[ai][1][0][0] * rr[0]; *(f32x4*)(hv + 4) = acc[ai][1][0][1] * rr[0]; }
;         if (m == 3 && fr >= 14) { float* tg = tailg + ((size_t)blk * 2 + (fr - 14)) * D_FF + f0;
;           *(f32x4*)tg = G[0]; *(f32x4*)(tg + 4) = G[1]; }
;         Gp[0] = G[0]; Gp[1] = G[1];
	v_pk_mul_f32 v[32:33], v[32:33], v[106:107]
	s_nop 0
	v_mul_f32_e32 v32, v32, v33
	v_cvt_pk_bf16_f32 v56, v32, v34
	v_mov_b64_e32 v[32:33], s[30:31]
	v_mad_i64_i32 v[34:35], s[22:23], v104, s26, v[32:33]
	v_lshl_add_u64 v[34:35], v[34:35], 0, v[124:125]
	v_cvt_pk_bf16_f32 v57, v86, v57
	v_cvt_pk_bf16_f32 v58, v59, v58
	v_cvt_pk_bf16_f32 v59, v77, v76
	global_store_dwordx4 v[34:35], v[56:59], off
	v_pk_mul_f32 v[34:35], v[50:51], v[102:103] op_sel_hi:[1,0]
	v_mov_b32_dpp v51, v73 row_ror:2 row_mask:0xf bank_mask:0xf
	v_mov_b32_dpp v50, v73 row_ror:1 row_mask:0xf bank_mask:0xf
	v_mov_b32_dpp v56, v82 row_ror:1 row_mask:0xf bank_mask:0xf
	v_mov_b32_dpp v51, v31 row_shr:2 row_mask:0xf bank_mask:0xf
	v_mov_b32_dpp v50, v31 row_shr:1 row_mask:0xf bank_mask:0xf
	v_fma_f32 v51, v63, v51, v55
	v_fmac_f32_e32 v51, v67, v50
	v_fmac_f32_e32 v51, v71, v31
	v_mul_f32_e32 v50, v51, v51
	v_fmamk_f32 v50, v50, 0xbdd2d3e6, v236
	v_mul_f32_e32 v50, v51, v50
	v_exp_f32_e32 v50, v50
	v_mov_b32_dpp v57, v82 row_ror:2 row_mask:0xf bank_mask:0xf
	v_mov_b32_dpp v82, v72 row_ror:1 row_mask:0xf bank_mask:0xf
	v_mov_b32_dpp v72, v72 row_ror:2 row_mask:0xf bank_mask:0xf
	v_add_f32_e32 v50, 1.0, v50
	v_rcp_f32_e32 v103, v50
	v_mov_b32_dpp v72, v30 row_shr:2 row_mask:0xf bank_mask:0xf
	v_mov_b32_dpp v82, v30 row_shr:1 row_mask:0xf bank_mask:0xf
	v_mov_b32_e32 v50, v23
	v_fma_f32 v23, v62, v72, v54
	v_fmac_f32_e32 v23, v66, v82
	v_pk_mul_f32 v[50:51], v[50:51], v[102:103]
	v_fmac_f32_e32 v23, v70, v30
	v_mul_f32_e32 v50, v50, v51
	v_mul_f32_e32 v51, v23, v23
	v_fmamk_f32 v51, v51, 0xbdd2d3e6, v236
	v_mul_f32_e32 v51, v23, v51
	v_exp_f32_e32 v51, v51
	v_mov_b32_dpp v75, v29 row_shr:2 row_mask:0xf bank_mask:0xf
	v_mov_b32_dpp v76, v80 row_ror:1 row_mask:0xf bank_mask:0xf
	v_mov_b32_dpp v77, v80 row_ror:2 row_mask:0xf bank_mask:0xf
	v_add_f32_e32 v51, 1.0, v51
	v_rcp_f32_e32 v103, v51
	v_mov_b32_dpp v80, v74 row_ror:1 row_mask:0xf bank_mask:0xf
	v_mov_b32_dpp v74, v74 row_ror:2 row_mask:0xf bank_mask:0xf
	v_mov_b32_dpp v79, v35 row_shr:2 row_mask:0xf bank_mask:0xf
	v_pk_mul_f32 v[22:23], v[22:23], v[102:103]
	v_mov_b32_dpp v74, v28 row_shr:2 row_mask:0xf bank_mask:0xf
	v_mul_f32_e32 v51, v22, v23
	v_fma_f32 v23, v61, v75, v53
	v_fmac_f32_e32 v23, v65, v81
	v_fmac_f32_e32 v23, v69, v29
	v_mul_f32_e32 v22, v23, v23
	v_fmamk_f32 v22, v22, 0xbdd2d3e6, v236
	v_mul_f32_e32 v22, v23, v22
	v_exp_f32_e32 v22, v22
	v_mov_b32_dpp v80, v28 row_shr:1 row_mask:0xf bank_mask:0xf
	v_mov_b32_dpp v78, v35 row_shr:1 row_mask:0xf bank_mask:0xf
	v_mov_b32_dpp v77, v34 row_shr:2 row_mask:0xf bank_mask:0xf
	v_add_f32_e32 v22, 1.0, v22
	v_rcp_f32_e32 v103, v22
	v_mov_b32_e32 v22, v21
	v_fma_f32 v21, v60, v74, v52
	v_fmac_f32_e32 v21, v64, v80
	v_pk_mul_f32 v[22:23], v[22:23], v[102:103]
	v_fmac_f32_e32 v21, v68, v28
	v_mul_f32_e32 v22, v22, v23
	v_mul_f32_e32 v23, v21, v21
	v_fmamk_f32 v23, v23, 0xbdd2d3e6, v236
	v_mul_f32_e32 v23, v21, v23
	v_exp_f32_e32 v23, v23
	v_mov_b32_dpp v76, v34 row_shr:1 row_mask:0xf bank_mask:0xf
	v_mov_b32_dpp v59, v83 row_ror:2 row_mask:0xf bank_mask:0xf
	v_mov_b32_dpp v58, v83 row_ror:1 row_mask:0xf bank_mask:0xf
	v_add_f32_e32 v23, 1.0, v23
	v_rcp_f32_e32 v103, v23
	v_mov_b32_dpp v59, v49 row_shr:2 row_mask:0xf bank_mask:0xf
	v_mov_b32_dpp v58, v49 row_shr:1 row_mask:0xf bank_mask:0xf
	v_mov_b32_dpp v57, v48 row_shr:2 row_mask:0xf bank_mask:0xf
	v_pk_mul_f32 v[20:21], v[20:21], v[102:103]
	v_mov_b32_dpp v56, v48 row_shr:1 row_mask:0xf bank_mask:0xf
	v_mul_f32_e32 v23, v20, v21
	v_fma_f32 v21, v39, v79, v27
	v_fmac_f32_e32 v21, v43, v78
	v_fmac_f32_e32 v21, v47, v35
	v_mul_f32_e32 v20, v21, v21
	v_fmamk_f32 v20, v20, 0xbdd2d3e6, v236
	v_mul_f32_e32 v20, v21, v20
	v_exp_f32_e32 v20, v20
	s_nop 0
	v_add_f32_e32 v20, 1.0, v20
	v_rcp_f32_e32 v103, v20
	v_mov_b32_e32 v20, v15
	v_fma_f32 v15, v38, v77, v26
	v_fmac_f32_e32 v15, v42, v76
	v_pk_mul_f32 v[20:21], v[20:21], v[102:103]
	v_fmac_f32_e32 v15, v46, v34
	v_mul_f32_e32 v20, v20, v21
	v_mul_f32_e32 v21, v15, v15
	v_fmamk_f32 v21, v21, 0xbdd2d3e6, v236
	v_mul_f32_e32 v21, v15, v21
	v_exp_f32_e32 v21, v21
	s_nop 0
	v_add_f32_e32 v21, 1.0, v21
	v_rcp_f32_e32 v103, v21
	s_nop 0
	v_pk_mul_f32 v[14:15], v[14:15], v[102:103]
	s_nop 0
	v_mul_f32_e32 v21, v14, v15
	v_fma_f32 v15, v37, v59, v25
	v_fmac_f32_e32 v15, v41, v58
	v_fmac_f32_e32 v15, v45, v49
	v_mul_f32_e32 v14, v15, v15
	v_fmamk_f32 v14, v14, 0xbdd2d3e6, v236
	v_mul_f32_e32 v14, v15, v14
	v_exp_f32_e32 v14, v14
	s_nop 0
	v_add_f32_e32 v14, 1.0, v14
	v_rcp_f32_e32 v103, v14
	v_mov_b32_e32 v14, v13
	v_fma_f32 v13, v36, v57, v24
	v_fmac_f32_e32 v13, v40, v56
	v_pk_mul_f32 v[14:15], v[14:15], v[102:103]
	v_fmac_f32_e32 v13, v44, v48
	v_mul_f32_e32 v14, v14, v15
	v_mul_f32_e32 v15, v13, v13
	v_fmamk_f32 v15, v15, 0xbdd2d3e6, v236
	v_mul_f32_e32 v15, v13, v15
	v_exp_f32_e32 v15, v15
	s_nop 0
	v_add_f32_e32 v15, 1.0, v15
	v_rcp_f32_e32 v103, v15
	s_nop 0
	v_pk_mul_f32 v[12:13], v[12:13], v[102:103]
	s_nop 0
	v_mul_f32_e32 v12, v12, v13
	v_cvt_pk_bf16_f32 v12, v12, v14
	v_cvt_pk_bf16_f32 v13, v21, v20
	v_mad_i64_i32 v[20:21], s[22:23], v100, s26, v[32:33]
	v_lshl_add_u64 v[20:21], v[20:21], 0, v[124:125]
	v_cvt_pk_bf16_f32 v14, v23, v22
	v_cvt_pk_bf16_f32 v15, v51, v50
	global_store_dwordx4 v[20:21], v[12:15], off
	v_mov_b32_dpp v50, v30 row_ror:1 row_mask:0xf bank_mask:0xf
; DI unsigned cvt_pk_bf16(float lo, float hi) { unsigned r; asm volatile("v_cvt_pk_bf16_f32 %0, %1, %2" : "=v"(r) : "v"(lo), "v"(hi)); return r; }
;   DI void operator()(const f32x4 (&acc)[2][2][4][2], const Unit& u, int wr, int wc, int fr, int fq) const {
;     ...
;       for (int m = 0; m < 4; ++m) {
;         float o[2][4];
;         f32x4 G[2];
; #pragma unroll
;         for (int n = 0; n < 2; ++n) G[n] = acc[ai][0][m][n] * rr[m];
; #pragma unroll
;         for (int n = 0; n < 2; ++n)
; #pragma unroll
;           for (int j = 0; j < 4; ++j) {
;             const float g0 = G[n][j], gp = Gp[n][j];
;             const float g1 = dpp_shr_or(dpp_ror(gp, 1), g0, 1);
;             const float g2 = dpp_shr_or(dpp_ror(gp, 2), g0, 2);
;             const float cv = __builtin_fmaf(w2[n][j], g0, __builtin_fmaf(w1[n][j], g1, __builtin_fmaf(w0[n][j], g2, bb[n][j])));
;             o[n][j] = gelu_tanh(cv) * (acc[ai][1][m][n][j] * rr[m]);
;           }
;         const bool head = (m == 0) && (fr < 2);
;         if (!head) { u32x4 w; w.x = cvt_pk_bf16(o[0][0], o[0][1]); w.y = cvt_pk_bf16(o[0][2], o[0][3]); w.z = cvt_pk_bf16(o[1][0], o[1][1]); w.w = cvt_pk_bf16(o[1][2], o[1][3]);
;           *(u32x4*)(act + (size_t)(rowb + m * 16 + fr) * D_FF + f0) = w; }
;         if (m == 0 && fr < 2) { float* hg = headg + ((size_t)blk * 2 + fr) * D_FF + f0; float* hv = headv + ((size_t)blk * 2 + fr) * D_FF + f0;
;           *(f32x4*)hg = G[0]; *(f32x4*)(hg + 4) = G[1]; *(f32x4*)hv = acc[ai][1][0][0] * rr[0]; *(f32x4*)(hv + 4) = acc[ai][1][0][1] * rr[0]; }
;         if (m == 3 && fr >= 14) { float* tg = tailg + ((size_t)blk * 2 + (fr - 14)) * D_FF + f0;
;           *(f32x4*)tg = G[0]; *(f32x4*)(tg + 4) = G[1]; }
	v_mov_b32_dpp v30, v30 row_ror:2 row_mask:0xf bank_mask:0xf
	v_pk_mul_f32 v[12:13], v[16:17], v[98:99] op_sel_hi:[1,0]
	v_mov_b32_dpp v17, v31 row_ror:2 row_mask:0xf bank_mask:0xf
	v_mov_b32_dpp v16, v31 row_ror:1 row_mask:0xf bank_mask:0xf
	v_pk_mul_f32 v[14:15], v[18:19], v[98:99] op_sel_hi:[1,0]
	v_mov_b32_dpp v17, v11 row_shr:2 row_mask:0xf bank_mask:0xf
	v_mov_b32_dpp v16, v11 row_shr:1 row_mask:0xf bank_mask:0xf
	v_fma_f32 v17, v63, v17, v55
	v_fmac_f32_e32 v17, v67, v16
	v_fmac_f32_e32 v17, v71, v11
	v_mul_f32_e32 v16, v17, v17
	v_fmamk_f32 v16, v16, 0xbdd2d3e6, v236
	v_mul_f32_e32 v16, v17, v16
	v_exp_f32_e32 v16, v16
	v_mov_b32_dpp v30, v10 row_shr:2 row_mask:0xf bank_mask:0xf
	v_mov_b32_dpp v50, v10 row_shr:1 row_mask:0xf bank_mask:0xf
	v_mov_b32_dpp v20, v49 row_ror:1 row_mask:0xf bank_mask:0xf
	v_add_f32_e32 v16, 1.0, v16
	v_rcp_f32_e32 v99, v16
	v_mov_b32_e32 v16, v7
	v_fma_f32 v7, v62, v30, v54
	v_fmac_f32_e32 v7, v66, v50
	v_pk_mul_f32 v[16:17], v[16:17], v[98:99]
	v_fmac_f32_e32 v7, v70, v10
	v_mul_f32_e32 v16, v16, v17
	v_mul_f32_e32 v17, v7, v7
	v_fmamk_f32 v17, v17, 0xbdd2d3e6, v236
	v_mul_f32_e32 v17, v7, v17
	v_exp_f32_e32 v17, v17
	v_mov_b32_dpp v21, v49 row_ror:2 row_mask:0xf bank_mask:0xf
	v_mov_b32_dpp v49, v29 row_ror:1 row_mask:0xf bank_mask:0xf
	v_mov_b32_dpp v29, v29 row_ror:2 row_mask:0xf bank_mask:0xf
	v_add_f32_e32 v17, 1.0, v17
	v_rcp_f32_e32 v99, v17
	v_mov_b32_dpp v29, v9 row_shr:2 row_mask:0xf bank_mask:0xf
	v_mov_b32_dpp v49, v9 row_shr:1 row_mask:0xf bank_mask:0xf
	v_mov_b32_dpp v18, v48 row_ror:1 row_mask:0xf bank_mask:0xf
	v_pk_mul_f32 v[6:7], v[6:7], v[98:99]
	v_mov_b32_dpp v19, v48 row_ror:2 row_mask:0xf bank_mask:0xf
	v_mul_f32_e32 v17, v6, v7
	v_fma_f32 v7, v61, v29, v53
	v_fmac_f32_e32 v7, v65, v49
	v_fmac_f32_e32 v7, v69, v9
	v_mul_f32_e32 v6, v7, v7
	v_fmamk_f32 v6, v6, 0xbdd2d3e6, v236
	v_mul_f32_e32 v6, v7, v6
	v_mov_b32_dpp v48, v28 row_ror:1 row_mask:0xf bank_mask:0xf
	v_mov_b32_dpp v28, v28 row_ror:2 row_mask:0xf bank_mask:0xf
	v_exp_f32_e32 v6, v6
	v_mov_b32_dpp v48, v8 row_shr:1 row_mask:0xf bank_mask:0xf
	v_mov_b32_dpp v28, v8 row_shr:2 row_mask:0xf bank_mask:0xf
	v_fmac_f32_e32 v52, v60, v28
	v_fmac_f32_e32 v52, v64, v48
	v_add_f32_e32 v6, 1.0, v6
	v_fmac_f32_e32 v52, v68, v8
	v_rcp_f32_e32 v99, v6
	v_mov_b32_e32 v6, v5
	v_mul_f32_e32 v5, v52, v52
	v_fmamk_f32 v5, v5, 0xbdd2d3e6, v236
	v_mul_f32_e32 v5, v52, v5
	v_exp_f32_e32 v5, v5
	v_pk_mul_f32 v[6:7], v[6:7], v[98:99]
	v_mov_b32_dpp v22, v34 row_ror:1 row_mask:0xf bank_mask:0xf
	v_mov_b32_dpp v23, v34 row_ror:2 row_mask:0xf bank_mask:0xf
	v_add_f32_e32 v5, 1.0, v5
	v_rcp_f32_e32 v99, v5
	v_mov_b32_dpp v34, v35 row_ror:1 row_mask:0xf bank_mask:0xf
	v_mov_b32_dpp v35, v35 row_ror:2 row_mask:0xf bank_mask:0xf
	v_mov_b32_e32 v5, v52
	v_pk_mul_f32 v[4:5], v[4:5], v[98:99]
	v_mov_b32_dpp v35, v15 row_shr:2 row_mask:0xf bank_mask:0xf
	v_mov_b32_dpp v34, v15 row_shr:1 row_mask:0xf bank_mask:0xf
	v_mul_f32_e32 v6, v6, v7
	v_mul_f32_e32 v7, v4, v5
	v_fma_f32 v5, v39, v35, v27
	v_fmac_f32_e32 v5, v43, v34
	v_fmac_f32_e32 v5, v47, v15
	v_mul_f32_e32 v4, v5, v5
	v_fmamk_f32 v4, v4, 0xbdd2d3e6, v236
	v_mul_f32_e32 v4, v5, v4
	v_exp_f32_e32 v4, v4
	v_mov_b32_dpp v23, v14 row_shr:2 row_mask:0xf bank_mask:0xf
	v_mov_b32_dpp v22, v14 row_shr:1 row_mask:0xf bank_mask:0xf
	v_mov_b32_dpp v21, v13 row_shr:2 row_mask:0xf bank_mask:0xf
	v_add_f32_e32 v4, 1.0, v4
	v_rcp_f32_e32 v99, v4
	v_mov_b32_e32 v4, v3
	v_fma_f32 v3, v38, v23, v26
	v_fmac_f32_e32 v3, v42, v22
	v_pk_mul_f32 v[4:5], v[4:5], v[98:99]
	v_fmac_f32_e32 v3, v46, v14
	v_mul_f32_e32 v4, v4, v5
	v_mul_f32_e32 v5, v3, v3
	v_fmamk_f32 v5, v5, 0xbdd2d3e6, v236
	v_mul_f32_e32 v5, v3, v5
	v_exp_f32_e32 v5, v5
	v_mov_b32_dpp v20, v13 row_shr:1 row_mask:0xf bank_mask:0xf
	v_mov_b32_dpp v19, v12 row_shr:2 row_mask:0xf bank_mask:0xf
	v_mov_b32_dpp v18, v12 row_shr:1 row_mask:0xf bank_mask:0xf
	v_add_f32_e32 v5, 1.0, v5
	v_rcp_f32_e32 v99, v5
	v_fmac_f32_e32 v24, v36, v19
	v_fmac_f32_e32 v24, v40, v18
	v_fmac_f32_e32 v24, v44, v12
	v_pk_mul_f32 v[2:3], v[2:3], v[98:99]
	s_nop 0
	v_mul_f32_e32 v5, v2, v3
	v_fma_f32 v3, v37, v21, v25
	v_fmac_f32_e32 v3, v41, v20
	v_fmac_f32_e32 v3, v45, v13
	v_mul_f32_e32 v2, v3, v3
	v_fmamk_f32 v2, v2, 0xbdd2d3e6, v236
	v_mul_f32_e32 v2, v3, v2
	v_exp_f32_e32 v2, v2
	s_nop 0
	v_add_f32_e32 v2, 1.0, v2
	v_rcp_f32_e32 v99, v2
	v_mov_b32_e32 v2, v1
	v_mul_f32_e32 v1, v24, v24
	v_fmamk_f32 v1, v1, 0xbdd2d3e6, v236
	v_mul_f32_e32 v1, v24, v1
	v_exp_f32_e32 v1, v1
	v_pk_mul_f32 v[2:3], v[2:3], v[98:99]
	v_add_f32_e32 v1, 1.0, v1
	v_rcp_f32_e32 v99, v1
	v_mov_b32_e32 v1, v24
	v_mul_f32_e32 v2, v2, v3
	v_pk_mul_f32 v[0:1], v[0:1], v[98:99]
	s_nop 0
	v_mul_f32_e32 v0, v0, v1
	v_cvt_pk_bf16_f32 v0, v0, v2
	v_cvt_pk_bf16_f32 v1, v5, v4
	v_mad_i64_i32 v[4:5], s[22:23], v96, s26, v[32:33]
	v_lshl_add_u64 v[4:5], v[4:5], 0, v[124:125]
	v_cvt_pk_bf16_f32 v2, v7, v6
	v_cvt_pk_bf16_f32 v3, v17, v16
	global_store_dwordx4 v[4:5], v[0:3], off
	s_and_saveexec_b64 s[22:23], s[36:37]
	s_cbranch_execz .LBB0_494
	v_lshl_add_u64 v[0:1], s[24:25], 0, v[168:169]
	v_mov_b64_e32 v[2:3], s[70:71]
	s_movk_i32 s26, 0x5800
	v_mad_u64_u32 v[2:3], s[24:25], v0, s26, v[2:3]
	v_mad_i32_i24 v3, v1, s26, v3
	v_lshl_add_u64 v[0:1], v[174:175], 2, v[2:3]
	global_store_dwordx4 v[0:1], v[12:15], off
	global_store_dwordx4 v[0:1], v[8:11], off offset:16

; #define LAS __attribute__((address_space(3)))
; #define MFMA32(a, b, c) __builtin_amdgcn_mfma_f32_32x32x16_bf16((a), (b), (c), 0, 0, 0)
; DI void sb_qblock(const bf16_t* __restrict__ PG, bf16_t* __restrict__ Osb, int b, int hh, int qb, LAS unsigned char* vl, int lane) {
;     ...
;   const int i16 = lane & 15, q4l = i16 >> 2, p4 = i16 & 3, gp = (lane >> 4) & 1;
;   LAS unsigned char* trb = vl + (4 * h + q4l) * 320 + (16 * gp + 4 * p4) * 2;
;     ...
;     const int s0 = kb * 32;
;     u32x4 vreg[8];
; #pragma unroll
;     for (int it = 0; it < 8; ++it) { const int idx = it * 64 + lane, row = idx >> 4, ch = idx & 15; vreg[it] = *(const u32x4*)(Vp + (size_t)(s0 + row) * PGW + ch * 8); }
;     f32x16 z;
; #pragma unroll
;     for (int i = 0; i < 16; ++i) z[i] = 0.f;
; #pragma unroll
;     for (int ks = 0; ks < 8; ++ks) z = MFMA32(kf[ks], qf[ks], z);
;     if (kb > 0) {
; #pragma unroll
;       for (int ks = 0; ks < 8; ++ks) kf[ks] = *(const bf16x8*)(Kp + (size_t)(s0 - 32 + r) * PGW + ks * 16 + 8 * h); }
;     const bool diag = (kb == qb);
;     float ls[16], lk[16];
; #pragma unroll
;     for (int i = 0; i < 16; ++i) { const int sl = (i & 3) + 8 * (i >> 2) + 4 * h; const float zz = z[i] * scale;
;       const float l = fminf(zz, 0.f) - __logf(1.0f + __expf(-fabsf(zz)));
;       ls[i] = l; const bool keep = !diag || (sl < r); lk[i] = keep ? (l - zz) : 0.f; }
; DI void sb_phase(const Ctx& cx, const bf16_t* PG, bf16_t* Osb, LAS unsigned char* lds) {
;   const int lane = TID & 63, wid = __builtin_amdgcn_readfirstlane(TID >> 6);
;   LAS unsigned char* vl = lds + wid * 10240;
;   for (int p = BID * 4 + (wid & 3); p < 1024; p += NBLK * 4) {
;     const int bh = p >> 5, i = p & 31;
;     const int qb = (wid < 4) ? i : 63 - i;
;     sb_qblock(PG, Osb, bh >> 3, bh & 7, qb, vl, lane);
.LBB0_897:
	s_and_b64 vcc, exec, s[0:1]
	s_cbranch_vccz .LBB0_936
	s_and_b32 s10, s8, 7
	s_lshl_b32 s10, s10, 5
	s_lshr_b32 s11, s8, 3
	s_or_b32 s8, s10, s11
	v_readfirstlane_b32 s0, v242
	s_ashr_i32 s1, s0, 6
	s_lshl_b32 s10, s8, 2
	s_and_b32 s0, s1, 3
	s_or_b32 s11, s0, s10
	v_bfe_u32 v218, v242, 5, 1
	s_cmpk_gt_i32 s11, 0x3ff
	v_and_b32_e32 v216, 31, v242
	v_lshrrev_b32_e32 v217, 2, v242
	v_and_b32_e32 v179, 16, v242
	v_lshlrev_b32_e32 v176, 3, v218
	v_lshlrev_b32_e32 v178, 2, v218
	s_cbranch_scc1 .LBB0_908
	v_and_b32_e32 v6, 64, v237
	s_waitcnt lgkmcnt(0)
	v_xor_b32_e32 v5, 32, v237
	v_add_u32_e32 v6, 64, v6
	v_cmp_lt_i32_e32 vcc, v5, v6
	s_mul_i32 s12, s1, 0x2800
	s_add_i32 s12, s12, 0
	v_cndmask_b32_e32 v5, v237, v5, vcc
	v_lshlrev_b32_e32 v219, 2, v5
	v_or_b32_e32 v5, 1, v178
	v_cmp_lt_u32_e64 s[38:39], v5, v216
	v_or_b32_e32 v5, 2, v178
	v_and_b32_e32 v1, 63, v242
	s_cmp_lt_i32 s1, 4
	v_and_or_b32 v2, v217, 3, v178
	v_mov_b32_e32 v3, s12
	s_movk_i32 s1, 0x140
	v_cmp_lt_u32_e64 s[40:41], v5, v216
	v_or_b32_e32 v5, 3, v178
	v_or_b32_e32 v6, 8, v178
	s_cselect_b64 s[88:89], -1, 0
	v_mad_u32_u24 v3, v2, s1, v3
	v_lshlrev_b32_e32 v2, 2, v242
	v_cmp_gt_u32_e64 s[34:35], 32, v1
	v_lshlrev_b32_e32 v1, 4, v242
	v_cmp_lt_u32_e64 s[42:43], v5, v216
	v_or_b32_e32 v5, 10, v178
	v_cmp_lt_u32_e64 s[46:47], v6, v216
	v_or_b32_e32 v6, 16, v178
	s_lshl_b32 s22, s5, 2
	v_readlane_b32 s1, v253, 63
	v_and_or_b32 v2, v2, 12, v179
	v_and_b32_e32 v1, 0xf0, v1
	v_or_b32_e32 v7, 11, v178
	v_or_b32_e32 v8, 9, v178
	v_cmp_lt_u32_e64 s[44:45], v5, v216
	v_or_b32_e32 v5, 18, v178
	v_cmp_lt_u32_e64 s[54:55], v6, v216
	v_or_b32_e32 v6, 24, v178
	s_add_u32 s24, s1, s92
	v_readlane_b32 s1, v254, 0
	v_lshlrev_b32_e32 v4, 1, v2
	v_lshlrev_b32_e32 v2, 3, v242
	v_add_u32_e32 v1, s12, v1
	v_bfe_u32 v220, v242, 4, 2
	v_cmp_lt_u32_e64 s[48:49], v7, v216
	v_cmp_lt_u32_e64 s[50:51], v8, v216
	v_or_b32_e32 v7, 19, v178
	v_or_b32_e32 v8, 17, v178
	v_cmp_lt_u32_e64 s[52:53], v5, v216
	v_or_b32_e32 v5, 26, v178
	v_cmp_lt_u32_e64 s[62:63], v6, v216
	v_lshrrev_b32_e32 v6, 1, v242
	s_addc_u32 s25, s1, s93
	s_lshl_b32 s1, s8, 5
	s_lshl_b32 s12, s0, 3
	v_mul_u32_u24_e32 v0, 0x3000, v216
	v_and_b32_e32 v2, 0x78, v2
	v_cmp_lt_u32_e64 s[56:57], v7, v216
	v_cmp_lt_u32_e64 s[58:59], v8, v216
	v_or_b32_e32 v7, 27, v178
	v_or_b32_e32 v8, 25, v178
	v_cmp_lt_u32_e64 s[60:61], v5, v216
	v_mul_u32_u24_e32 v5, 0x140, v220
	v_and_b32_e32 v208, 16, v6
	s_or_b32 s23, s1, s12
	s_lshl_b32 s1, s8, 4
	s_lshl_b32 s0, s0, 2
	v_or_b32_e32 v177, 0xffffffe0, v242
	v_or_b32_e32 v221, 4, v220
	v_or_b32_e32 v222, 8, v220
	v_or_b32_e32 v223, 12, v220
	v_or_b32_e32 v224, 16, v220
	v_or_b32_e32 v225, 20, v220
	v_or_b32_e32 v226, 24, v220
	v_or_b32_e32 v227, 28, v220
	v_cmp_lt_u32_e64 s[36:37], v178, v216
	v_cmp_lt_u32_e64 s[64:65], v7, v216
	v_cmp_lt_u32_e64 s[66:67], v8, v216
	v_lshl_add_u64 v[180:181], s[24:25], 0, v[208:209]
	s_lshl_b32 s26, s5, 5
	s_or_b32 s27, s1, s0
	s_lshl_b32 s72, s5, 4
	v_lshlrev_b32_e32 v182, 1, v0
	v_lshlrev_b32_e32 v184, 1, v176
	v_lshlrev_b32_e32 v186, 1, v2
	v_lshlrev_b32_e32 v188, 1, v178
	v_add_u32_e32 v228, v1, v5
	v_add_u32_e32 v229, v3, v4
	s_branch .LBB0_901

; #define LAS __attribute__((address_space(3)))
; DI float bf_lo(unsigned w) { return __uint_as_float(w << 16); }
; DI void gm_unit(const Ctx& cx, const bf16_t* __restrict__ PG, bf16_t* __restrict__ Ogm, const float* __restrict__ gvn, const float* __restrict__ ws, const float* __restrict__ bs, int unit, LAS unsigned char* lds) {
;   const int tid = TID, lane = tid & 63, wi = __builtin_amdgcn_readfirstlane(tid >> 6);
;   const int r = lane & 31, h = lane >> 5;
;   const int gh = unit & 1, bc = unit >> 1;
;   const int tok0 = (bc >> 4) * SEQ + (bc & 15) * 128;
;   LAS float* rinv = (LAS float*)(lds + 49152);
;   { const int tt = tid >> 2, part = tid & 3; const bf16_t* vp = PG + (size_t)(tok0 + tt) * PGW + 4096; float ss = 0.f;
; #pragma unroll 8
;     for (int i = 0; i < 32; ++i) { const u32x4 w = *(const u32x4*)(vp + (i * 4 + part) * 8);
;       float g;
;       g = bf_lo(w.x); ss += g * g; g = bf_hi(w.x); ss += g * g; g = bf_lo(w.y); ss += g * g; g = bf_hi(w.y); ss += g * g;
;       g = bf_lo(w.z); ss += g * g; g = bf_hi(w.z); ss += g * g; g = bf_lo(w.w); ss += g * g; g = bf_hi(w.w); ss += g * g; }
;     ss += __shfl_xor(ss, 1); ss += __shfl_xor(ss, 2);
;     if (part == 0) rinv[tt] = rsqrtf(ss * (1.0f / 1024.0f) + EPS); }
;   __syncthreads();
;   const int tb = wi & 3, dbp = wi >> 2;
;   const int i16 = lane & 15, q4l = i16 >> 2, p4 = i16 & 3, gp = (lane >> 4) & 1;
;   LAS unsigned char* trb = lds + (8 * h + q4l) * 320 + (16 * gp + 4 * p4) * 2;
;   const int t = tb * 32 + r;
;   const int chn = tid & 15, srow = tid >> 4;
; DI void run_phase(const Params& p, int ph, LAS unsigned char* lds, int wid_s) {
;     ...
;     __syncthreads();
;     if ((MIX_REP & 1) && l == 0) { sb_phase(cx, PG, Ob, lds); __syncthreads(); }
;     if ((MIX_REP & 2) && l == 0) { for (int u = BID; u < 128; u += NBLK)
;       gm_unit(cx, PG, Ob + (size_t)NTOK * 1024, p.in[4] + (size_t)l * 1024, p.in[5] + (size_t)l * 8 * 128 * 128, p.in[6] + (size_t)l * 8 * 128, u, lds); }
;     if ((MIX_REP & 4) && l == 0) { for (int u = (int)((BID + (NBLK >> 1)) % NBLK); u < 128; u += NBLK)
;       xa_unit(cx, PG, memkv + (size_t)l * 1024 * 2048, Ob + (size_t)2 * NTOK * 1024, u, lds); }
;     ...
;     for (int u = BID; u < 128; u += NBLK)
;       gm_unit(cx, PG, Ob + (size_t)NTOK * 1024, p.in[4] + (size_t)l * 1024, p.in[5] + (size_t)l * 8 * 128 * 128, p.in[6] + (size_t)l * 8 * 128, u, lds);
.LBB0_908:
	v_readlane_b32 s8, v254, 57
	s_nop 1
	s_lshl_b32 s10, s8, 2
	v_readlane_b32 s48, v252, 0
	v_readlane_b32 s52, v254, 31
	v_readlane_b32 s50, v252, 2
	v_readlane_b32 s51, v252, 3
	v_ashrrev_i32_e32 v88, 4, v242
	s_movk_i32 s0, 0x140
	v_readlane_b32 s56, v254, 35
	v_readlane_b32 s57, v254, 36
	v_readlane_b32 s58, v254, 37
	v_readlane_b32 s88, v254, 47
	v_readlane_b32 s50, v254, 49
	v_readlane_b32 s44, v254, 51
	v_readlane_b32 s46, v254, 53
	s_cmpk_gt_i32 s8, 0x7f
	v_mul_lo_u32 v166, v88, s0
	v_readlane_b32 s53, v254, 32
	v_readlane_b32 s54, v254, 33
	v_readlane_b32 s55, v254, 34
	v_readlane_b32 s60, v254, 39
	v_readlane_b32 s61, v254, 40
	v_readlane_b32 s62, v254, 41
	v_readlane_b32 s63, v254, 42
	v_readlane_b32 s66, v254, 45
	v_readlane_b32 s67, v254, 46
	v_readlane_b32 s49, v252, 1
	v_readlane_b32 s89, v254, 48
	v_readlane_b32 s51, v254, 50
	v_readlane_b32 s45, v254, 52
	v_readlane_b32 s47, v254, 54
	v_readlane_b32 s56, v254, 55
	s_movk_i32 s57, 0x3ff
	v_readlane_b32 s58, v254, 56
	s_waitcnt vmcnt(0) lgkmcnt(0)
	s_barrier
	v_readlane_b32 s59, v254, 38
	v_readlane_b32 s64, v254, 43
	v_readlane_b32 s65, v254, 44
	s_cbranch_scc1 .LBB0_933
	v_readlane_b32 s0, v254, 58
	v_readlane_b32 s1, v254, 59
	s_lshl_b64 s[22:23], s[0:1], 12
	s_lshl_b64 s[24:25], s[0:1], 19
	v_and_b32_e32 v2, 64, v237
	v_readlane_b32 s0, v254, 1
	v_and_b32_e32 v1, 3, v242
	v_xor_b32_e32 v0, 1, v237
	v_add_u32_e32 v2, 64, v2
	s_add_u32 s0, s0, s92
	v_readlane_b32 s1, v254, 2
	v_cmp_lt_i32_e32 vcc, v0, v2
	v_lshlrev_b32_e32 v208, 4, v1
	s_addc_u32 s1, s1, s93
	v_cndmask_b32_e32 v0, v237, v0, vcc
	v_lshl_add_u64 v[92:93], s[0:1], 0, v[208:209]
	s_lshl_b32 s11, s8, 6
	s_lshl_b32 s26, s5, 6
	s_lshl_b32 s27, s5, 2
	v_readlane_b32 s0, v254, 3
	v_lshlrev_b32_e32 v89, 2, v0
	v_xor_b32_e32 v0, 2, v237
	s_add_u32 s0, s0, s92
	v_readlane_b32 s1, v254, 4
	v_readlane_b32 s72, v254, 10
	v_cmp_lt_i32_e32 vcc, v0, v2
	s_addc_u32 s1, s1, s93
	v_readlane_b32 s82, v254, 20
	v_cndmask_b32_e32 v0, v237, v0, vcc
	v_readlane_b32 s83, v254, 21
	s_add_u32 s24, s82, s24
	v_lshlrev_b32_e32 v136, 2, v0
	v_and_b32_e32 v0, -4, v242
	v_lshlrev_b32_e32 v2, 2, v242
	v_readlane_b32 s84, v254, 22
	s_addc_u32 s25, s83, s25
	v_add_u32_e32 v137, 0, v0
	v_and_or_b32 v0, v217, 3, v176
	v_and_or_b32 v2, v2, 12, v179
	v_readlane_b32 s85, v254, 23
	s_add_u32 s30, s84, s22
	v_mul_u32_u24_e32 v0, 0x140, v0
	v_lshlrev_b32_e32 v2, 1, v2
	v_lshlrev_b32_e32 v208, 5, v218
	s_addc_u32 s31, s85, s23
	v_readlane_b32 s12, v254, 5
	v_add3_u32 v138, 0, v0, v2
	v_and_b32_e32 v2, 15, v242
	v_lshl_add_u64 v[94:95], s[24:25], 0, v[208:209]
	s_add_u32 s24, s12, s92
	v_readlane_b32 s12, v254, 6
	v_cmp_eq_u32_e64 s[34:35], 0, v1
	v_lshlrev_b32_e32 v0, 4, v2
	v_mov_b32_e32 v1, v209
	s_addc_u32 s25, s12, s93
	v_readlane_b32 s12, v254, 7
	v_lshl_add_u64 v[96:97], s[24:25], 0, v[0:1]
	s_add_u32 s24, s12, s92
	v_readlane_b32 s12, v254, 8
	s_addc_u32 s25, s12, s93
	v_readlane_b32 s12, v254, 9
	s_add_u32 s22, s12, s22
	v_readlane_b32 s12, v254, 26
	v_ashrrev_i32_e32 v90, 2, v242
	v_mov_b32_e32 v177, v209
	v_add_u32_e32 v3, 0, v0
	v_lshlrev_b32_e32 v4, 7, v216
	v_lshlrev_b32_e32 v208, 5, v2
	s_addc_u32 s23, s12, s23
	v_lshl_add_u32 v139, v88, 2, 0
	v_ashrrev_i32_e32 v91, 31, v90
	v_add_u32_e32 v140, 32, v88
	v_add_u32_e32 v141, 64, v88
	v_add_u32_e32 v142, 0x60, v88
	v_lshl_add_u64 v[98:99], s[24:25], 0, v[176:177]
	v_lshl_add_u64 v[100:101], s[22:23], 0, v[208:209]
	v_lshlrev_b32_e32 v143, 2, v4
	v_add_u32_e32 v144, v3, v166
	s_mov_b32 s40, s8
	v_readlane_b32 s73, v254, 11
	v_readlane_b32 s74, v254, 12
	v_readlane_b32 s75, v254, 13
	v_readlane_b32 s76, v254, 14
	v_readlane_b32 s77, v254, 15
	v_readlane_b32 s78, v254, 16
	v_readlane_b32 s79, v254, 17
	v_readlane_b32 s80, v254, 18
	v_readlane_b32 s81, v254, 19
	v_readlane_b32 s86, v254, 24
	v_readlane_b32 s87, v254, 25
	s_branch .LBB0_911
